# adds: next tile's first three K-fragment read pairs issued right after the tile-boundary barrier (under the trailing PV MFMAs) in the MLA loop
# speedup vs baseline: 1.0051x; 1.0051x over previous
.LBB0_1424:
	s_mov_b64 s[6:7], 0x80080
	v_lshl_add_u64 v[174:175], v[50:51], 0, s[30:31]
	v_lshl_add_u64 v[176:177], v[50:51], 0, s[6:7]
	s_nop 4
	v_max_f32_e32 v50, v35, v35
	v_max_f32_e32 v51, v34, v34
	v_max_f32_e32 v50, v51, v50
	v_max3_f32 v51, v36, v37, v19
	v_max3_f32 v50, v50, v18, v20
	v_max3_f32 v50, v50, v21, v38
	v_max3_f32 v51, v51, v40, v41
	v_max3_f32 v50, v50, v39, v22
	v_max3_f32 v51, v51, v24, v25
	v_max3_f32 v50, v50, v23, v42
	v_max3_f32 v51, v51, v44, v45
	v_max3_f32 v50, v50, v43, v26
	v_max3_f32 v51, v51, v28, v29
	v_max3_f32 v50, v50, v27, v46
	v_max3_f32 v51, v51, v48, v49
	v_max3_f32 v50, v50, v47, v30
	v_max3_f32 v51, v51, v32, v33
	v_max3_f32 v50, v50, v31, v51
	v_mov_b32_e32 v51, v50
	s_nop 1
	v_permlane32_swap_b32_e32 v50, v51
	v_max_f32_e32 v51, v51, v51
	v_max_f32_e32 v50, v50, v50
	v_max_f32_e32 v50, v50, v51
	v_sub_f32_e32 v34, v34, v50
	v_sub_f32_e32 v18, v18, v50
	v_sub_f32_e32 v35, v35, v50
	v_sub_f32_e32 v19, v19, v50
	v_sub_f32_e32 v36, v36, v50
	v_sub_f32_e32 v20, v20, v50
	v_sub_f32_e32 v37, v37, v50
	v_sub_f32_e32 v21, v21, v50
	v_sub_f32_e32 v38, v38, v50
	v_sub_f32_e32 v22, v22, v50
	v_sub_f32_e32 v39, v39, v50
	v_sub_f32_e32 v23, v23, v50
	v_sub_f32_e32 v40, v40, v50
	v_sub_f32_e32 v24, v24, v50
	v_sub_f32_e32 v41, v41, v50
	v_sub_f32_e32 v25, v25, v50
	v_sub_f32_e32 v42, v42, v50
	v_sub_f32_e32 v26, v26, v50
	v_sub_f32_e32 v43, v43, v50
	v_sub_f32_e32 v27, v27, v50
	v_sub_f32_e32 v44, v44, v50
	v_sub_f32_e32 v28, v28, v50
	v_sub_f32_e32 v45, v45, v50
	v_sub_f32_e32 v29, v29, v50
	v_sub_f32_e32 v46, v46, v50
	v_sub_f32_e32 v30, v30, v50
	v_sub_f32_e32 v47, v47, v50
	v_sub_f32_e32 v31, v31, v50
	v_sub_f32_e32 v48, v48, v50
	v_sub_f32_e32 v32, v32, v50
	v_sub_f32_e32 v49, v49, v50
	v_sub_f32_e32 v33, v33, v50
	v_add_f32_e32 v198, 0, v50
	v_exp_f32_e32 v34, v34
	v_exp_f32_e32 v18, v18
	v_exp_f32_e32 v35, v35
	v_exp_f32_e32 v19, v19
	v_add_f32_e32 v50, v34, v18
	v_add_f32_e32 v51, v35, v19
	s_and_b32 s0, s82, 0x3fffffc0
	v_lshl_add_u64 v[168:169], v[52:53], 0, v[162:163]
	v_exp_f32_e32 v36, v36
	v_exp_f32_e32 v20, v20
	v_exp_f32_e32 v37, v37
	v_exp_f32_e32 v21, v21
	v_exp_f32_e32 v38, v38
	v_exp_f32_e32 v39, v39
	v_add_f32_e32 v52, v36, v20
	v_add_f32_e32 v53, v37, v21
	v_add_f32_e32 v50, v50, v38
	v_add_f32_e32 v51, v51, v39
	s_lshl_b32 s0, s0, 2
	v_exp_f32_e32 v22, v22
	v_exp_f32_e32 v23, v23
	v_exp_f32_e32 v40, v40
	v_exp_f32_e32 v41, v41
	v_add_f32_e32 v52, v52, v40
	v_add_f32_e32 v53, v53, v41
	v_add_f32_e32 v50, v50, v22
	v_add_f32_e32 v51, v51, v23
	s_add_i32 s0, s0, 0
	v_lshlrev_b32_e32 v58, 1, v98
	s_addk_i32 s85, 0x100
	v_exp_f32_e32 v24, v24
	v_exp_f32_e32 v25, v25
	v_exp_f32_e32 v42, v42
	v_exp_f32_e32 v43, v43
	v_add_f32_e32 v52, v52, v24
	v_add_f32_e32 v53, v53, v25
	v_add_f32_e32 v50, v50, v42
	v_add_f32_e32 v51, v51, v43
	s_add_i32 s0, s0, 0x14000
	v_and_b32_e32 v58, 32, v58
	s_movk_i32 s1, 0xc0
	s_lshr_b32 s10, s85, 6
	v_sub_f32_e32 v82, 0, v198
	v_exp_f32_e32 v26, v26
	v_exp_f32_e32 v27, v27
	v_exp_f32_e32 v44, v44
	v_exp_f32_e32 v28, v28
	v_exp_f32_e32 v45, v45
	v_exp_f32_e32 v29, v29
	v_exp_f32_e32 v46, v46
	v_exp_f32_e32 v30, v30
	v_exp_f32_e32 v47, v47
	v_exp_f32_e32 v31, v31
	v_exp_f32_e32 v48, v48
	v_exp_f32_e32 v32, v32
	v_exp_f32_e32 v49, v49
	v_exp_f32_e32 v33, v33
	v_add_f32_e32 v52, v52, v44
	v_add_f32_e32 v53, v53, v45
	v_add_f32_e32 v50, v50, v26
	v_add_f32_e32 v51, v51, v27
	v_and_or_b32 v58, v62, s1, v58
	v_and_b32_e32 v59, 0x100, v60
	s_cmp_lg_u32 0, -1
	v_mov_b32_e32 v83, v82
	v_mov_b32_e32 v84, v82
	v_mov_b32_e32 v85, v82
	v_mov_b32_e32 v86, v82
	v_mov_b32_e32 v87, v82
	v_mov_b32_e32 v88, v82
	v_mov_b32_e32 v89, v82
	v_mov_b32_e32 v90, v82
	v_mov_b32_e32 v91, v82
	v_mov_b32_e32 v92, v82
	v_mov_b32_e32 v93, v82
	v_mov_b32_e32 v94, v82
	v_mov_b32_e32 v95, v82
	v_mov_b32_e32 v96, v82
	v_mov_b32_e32 v97, v82
	v_add_f32_e32 v52, v52, v28
	v_add_f32_e32 v53, v53, v29
	v_add_f32_e32 v50, v50, v46
	v_add_f32_e32 v51, v51, v47
	v_or3_b32 v58, v58, v59, v61
	s_cselect_b32 s1, 0, 0
	v_add_f32_e32 v52, v52, v48
	v_add_f32_e32 v53, v53, v49
	v_add_f32_e32 v50, v50, v30
	v_add_f32_e32 v51, v51, v31
	v_cvt_pk_bf16_f32 v66, v34, v35
	v_cvt_pk_bf16_f32 v67, v36, v37
	v_cvt_pk_bf16_f32 v68, v38, v39
	v_cvt_pk_bf16_f32 v69, v40, v41
	v_add_u32_e32 v190, s1, v58
	v_lshl_add_u64 v[170:171], v[54:55], 0, v[164:165]
	v_lshl_add_u64 v[172:173], v[56:57], 0, v[166:167]
	v_add_f32_e32 v52, v52, v32
	v_add_f32_e32 v53, v53, v33
	v_add_f32_e32 v50, v50, v51
	v_permlane32_swap_b32_e32 v66, v68
	v_add_f32_e32 v51, v52, v53
	v_permlane32_swap_b32_e32 v67, v69
	v_add_f32_e32 v99, v50, v51
	v_cvt_pk_bf16_f32 v100, v42, v43
	v_cvt_pk_bf16_f32 v101, v44, v45
	v_cvt_pk_bf16_f32 v102, v46, v47
	v_cvt_pk_bf16_f32 v103, v48, v49
	v_cvt_pk_bf16_f32 v104, v18, v19
	s_nop 0
	v_mov_b32_e32 v128, v99
	v_cvt_pk_bf16_f32 v105, v20, v21
	v_cvt_pk_bf16_f32 v106, v22, v23
	v_cvt_pk_bf16_f32 v107, v24, v25
	v_cvt_pk_bf16_f32 v108, v26, v27
	v_cvt_pk_bf16_f32 v109, v28, v29
	v_cvt_pk_bf16_f32 v110, v30, v31
	v_cvt_pk_bf16_f32 v111, v32, v33
	s_nop 1
	v_permlane32_swap_b32_e32 v99, v128
	v_permlane32_swap_b32_e32 v100, v102
	v_permlane32_swap_b32_e32 v101, v103
	v_permlane32_swap_b32_e32 v104, v106
	v_permlane32_swap_b32_e32 v105, v107
	v_permlane32_swap_b32_e32 v108, v110
	v_permlane32_swap_b32_e32 v109, v111
	ds_read_b64_tr_b16 v[18:19], v190 offset:0
	ds_read_b64_tr_b16 v[20:21], v190 offset:0x800
	ds_read_b64_tr_b16 v[34:35], v190 offset:0x1000
	ds_read_b64_tr_b16 v[36:37], v190 offset:0x1800
	ds_read_b64_tr_b16 v[38:39], v190 offset:0x2000
	ds_read_b64_tr_b16 v[40:41], v190 offset:0x2800
	ds_read_b64_tr_b16 v[42:43], v190 offset:0x3000
	ds_read_b64_tr_b16 v[44:45], v190 offset:0x3800
	ds_read_b64_tr_b16 v[46:47], v190 offset:0x200
	ds_read_b64_tr_b16 v[48:49], v190 offset:0xa00
	ds_read_b64_tr_b16 v[50:51], v190 offset:0x1200
	ds_read_b64_tr_b16 v[52:53], v190 offset:0x1a00
	ds_read_b64_tr_b16 v[54:55], v190 offset:0x2200
	ds_read_b64_tr_b16 v[56:57], v190 offset:0x2a00
	ds_read_b64_tr_b16 v[58:59], v190 offset:0x3200
	ds_read_b64_tr_b16 v[60:61], v190 offset:0x3a00
	s_waitcnt lgkmcnt(8)
	s_nop 0
	v_mfma_f32_32x32x16_bf16 v[18:33], v[66:69], v[18:21], 0
	v_mfma_f32_32x32x16_bf16 v[18:33], v[100:103], v[34:37], v[18:33]
	v_mfma_f32_32x32x16_bf16 v[18:33], v[104:107], v[38:41], v[18:33]
	v_mfma_f32_32x32x16_bf16 v[18:33], v[108:111], v[42:45], v[18:33]
	ds_read_b64_tr_b16 v[62:63], v190 offset:0x400
	ds_read_b64_tr_b16 v[64:65], v190 offset:0xc00
	ds_read_b64_tr_b16 v[70:71], v190 offset:0x1400
	ds_read_b64_tr_b16 v[72:73], v190 offset:0x1c00
	ds_read_b64_tr_b16 v[74:75], v190 offset:0x2400
	ds_read_b64_tr_b16 v[76:77], v190 offset:0x2c00
	ds_read_b64_tr_b16 v[78:79], v190 offset:0x3400
	ds_read_b64_tr_b16 v[80:81], v190 offset:0x3c00
	s_waitcnt lgkmcnt(8)
	v_mfma_f32_32x32x16_bf16 v[34:49], v[66:69], v[46:49], 0
	v_mfma_f32_32x32x16_bf16 v[34:49], v[100:103], v[50:53], v[34:49]
	v_mfma_f32_32x32x16_bf16 v[34:49], v[104:107], v[54:57], v[34:49]
	v_mfma_f32_32x32x16_bf16 v[34:49], v[108:111], v[58:61], v[34:49]
	ds_read_b64_tr_b16 v[112:113], v190 offset:0x600
	ds_read_b64_tr_b16 v[114:115], v190 offset:0xe00
	ds_read_b64_tr_b16 v[116:117], v190 offset:0x1600
	ds_read_b64_tr_b16 v[118:119], v190 offset:0x1e00
	ds_read_b64_tr_b16 v[120:121], v190 offset:0x2600
	ds_read_b64_tr_b16 v[122:123], v190 offset:0x2e00
	ds_read_b64_tr_b16 v[124:125], v190 offset:0x3600
	ds_read_b64_tr_b16 v[126:127], v190 offset:0x3e00
	s_waitcnt lgkmcnt(8)
	v_mfma_f32_32x32x16_bf16 v[50:65], v[66:69], v[62:65], 0
	v_mfma_f32_32x32x16_bf16 v[50:65], v[100:103], v[70:73], v[50:65]
	v_mfma_f32_32x32x16_bf16 v[50:65], v[104:107], v[74:77], v[50:65]
	v_mfma_f32_32x32x16_bf16 v[50:65], v[108:111], v[78:81], v[50:65]
	s_waitcnt lgkmcnt(0)
	v_mfma_f32_32x32x16_bf16 v[66:81], v[66:69], v[112:115], 0
	s_waitcnt vmcnt(0)
	v_lshl_add_u32 v191, v189, 2, s0
	v_lshl_add_u32 v188, v186, 2, s0
	s_add_i32 s0, s96, 0xffffff65
	v_add_f32_e32 v99, v99, v128
	v_cmp_gt_u32_e64 s[6:7], 32, v98
	v_add_u32_e32 v98, s0, v189
	v_mfma_f32_32x32x16_bf16 v[66:81], v[100:103], v[116:119], v[66:81]
	v_add_f32_e32 v199, 0, v99
	v_add_u32_e32 v211, 0xe000, v194
	v_add_u32_e32 v210, 0xe000, v195
	v_add_u32_e32 v209, 0xe000, v196
	v_add_u32_e32 v208, 0xe000, v197
	v_add_u32_e32 v207, 0xe080, v194
	v_add_u32_e32 v206, 0xe080, v195
	v_mfma_f32_32x32x16_bf16 v[66:81], v[104:107], v[120:123], v[66:81]
	v_add_u32_e32 v205, 0xe080, v196
	v_add_u32_e32 v204, 0xe080, v197
	v_add_u32_e32 v203, 0xe100, v194
	v_add_u32_e32 v202, 0xe100, v195
	v_add_u32_e32 v201, 0xe100, v196
	v_add_u32_e32 v200, 0xe100, v197
	v_sub_u32_e32 v212, v98, v186
	v_mfma_f32_32x32x16_bf16 v[66:81], v[108:111], v[124:127], v[66:81]
	s_movk_i32 s12, 0xbf
	s_mov_b32 s11, 3
	s_barrier
	ds_read_b128 v[178:181], v211
	ds_read_b128 v[214:217], v211 offset:12288
	ds_read_b128 v[238:241], v210
	ds_read_b128 v[242:245], v210 offset:12288
	ds_read_b128 v[246:249], v209
	ds_read_b128 v[250:253], v209 offset:12288
.LBB0_1425:
	s_add_i32 s13, s74, 0x8000
	s_mov_b32 s14, m0
	s_mov_b32 m0, s13
	s_nop 0
	global_load_lds_dwordx4 v[168:169], off
	s_mov_b32 m0, s14
	ds_read_b128 v[218:221], v193
	ds_read_b128 v[222:225], v193 offset:1024
	ds_read_b128 v[226:229], v193 offset:2048
	ds_read_b128 v[230:233], v193 offset:3072
	s_waitcnt lgkmcnt(9)
	v_mfma_f32_32x32x16_bf16 v[114:129], v[178:181], v[158:161], v[82:97]
	s_waitcnt lgkmcnt(8)
	v_mfma_f32_32x32x16_bf16 v[98:113], v[214:217], v[158:161], v[82:97]
	ds_read_b128 v[178:181], v208
	ds_read_b128 v[214:217], v208 offset:12288
	s_waitcnt lgkmcnt(9)
	v_mfma_f32_32x32x16_bf16 v[114:129], v[238:241], v[154:157], v[114:129]
	s_waitcnt lgkmcnt(8)
	v_mfma_f32_32x32x16_bf16 v[98:113], v[242:245], v[154:157], v[98:113]
	ds_read_b128 v[238:241], v207
	ds_read_b128 v[242:245], v207 offset:12288
	s_waitcnt lgkmcnt(9)
	v_mfma_f32_32x32x16_bf16 v[114:129], v[246:249], v[150:153], v[114:129]
	s_waitcnt lgkmcnt(8)
	v_mfma_f32_32x32x16_bf16 v[98:113], v[250:253], v[150:153], v[98:113]
	ds_read_b128 v[246:249], v206
	ds_read_b128 v[250:253], v206 offset:12288
	s_waitcnt lgkmcnt(5)
	v_mfma_f32_32x32x16_bf16 v[114:129], v[178:181], v[146:149], v[114:129]
	s_waitcnt lgkmcnt(4)
	v_mfma_f32_32x32x16_bf16 v[98:113], v[214:217], v[146:149], v[98:113]
	ds_read_b128 v[178:181], v205
	ds_read_b128 v[214:217], v205 offset:12288
	s_waitcnt lgkmcnt(5)
	v_mfma_f32_32x32x16_bf16 v[114:129], v[238:241], v[142:145], v[114:129]
	s_waitcnt lgkmcnt(4)
	v_mfma_f32_32x32x16_bf16 v[98:113], v[242:245], v[142:145], v[98:113]
	ds_read_b128 v[238:241], v204
	ds_read_b128 v[242:245], v204 offset:12288
	s_waitcnt lgkmcnt(5)
	v_mfma_f32_32x32x16_bf16 v[114:129], v[246:249], v[138:141], v[114:129]
	s_waitcnt lgkmcnt(4)
	v_mfma_f32_32x32x16_bf16 v[98:113], v[250:253], v[138:141], v[98:113]
	ds_read_b128 v[246:249], v203
	ds_read_b128 v[250:253], v203 offset:12288
	s_add_i32 s13, s75, 0x8000
	s_mov_b32 s14, m0
	s_mov_b32 m0, s13
	s_nop 0
	global_load_lds_dwordx4 v[170:171], off
	s_mov_b32 m0, s14
	s_waitcnt lgkmcnt(5)
	v_mfma_f32_32x32x16_bf16 v[114:129], v[178:181], v[134:137], v[114:129]
	s_waitcnt lgkmcnt(4)
	v_mfma_f32_32x32x16_bf16 v[98:113], v[214:217], v[134:137], v[98:113]
	ds_read_b128 v[178:181], v202
	ds_read_b128 v[214:217], v202 offset:12288
	s_waitcnt lgkmcnt(5)
	v_mfma_f32_32x32x16_bf16 v[114:129], v[238:241], v[130:133], v[114:129]
	s_waitcnt lgkmcnt(4)
	v_mfma_f32_32x32x16_bf16 v[98:113], v[242:245], v[130:133], v[98:113]
	ds_read_b128 v[238:241], v201
	ds_read_b128 v[242:245], v201 offset:12288
	s_waitcnt lgkmcnt(5)
	v_mfma_f32_32x32x16_bf16 v[114:129], v[246:249], v[218:221], v[114:129]
	s_waitcnt lgkmcnt(4)
	v_mfma_f32_32x32x16_bf16 v[98:113], v[250:253], v[218:221], v[98:113]
	ds_read_b128 v[246:249], v200
	ds_read_b128 v[250:253], v200 offset:12288
	s_waitcnt lgkmcnt(5)
	v_mfma_f32_32x32x16_bf16 v[114:129], v[178:181], v[222:225], v[114:129]
	s_waitcnt lgkmcnt(4)
	v_mfma_f32_32x32x16_bf16 v[98:113], v[214:217], v[222:225], v[98:113]
	s_waitcnt lgkmcnt(3)
	v_mfma_f32_32x32x16_bf16 v[114:129], v[238:241], v[226:229], v[114:129]
	s_waitcnt lgkmcnt(2)
	v_mfma_f32_32x32x16_bf16 v[98:113], v[242:245], v[226:229], v[98:113]
	s_waitcnt lgkmcnt(1)
	v_mfma_f32_32x32x16_bf16 v[114:129], v[246:249], v[230:233], v[114:129]
	s_waitcnt lgkmcnt(0)
	v_mfma_f32_32x32x16_bf16 v[98:113], v[250:253], v[230:233], v[98:113]
	s_add_i32 s13, s5, 0x8000
	s_mov_b32 s14, m0
	s_mov_b32 m0, s13
	s_nop 0
	global_load_lds_dwordx4 v[172:173], off
	s_mov_b32 m0, s14
	s_sub_i32 s0, s12, 64
	s_cmp_le_i32 s0, s96
	s_cbranch_scc1 .LBB0_1427
	v_add_u32_e32 v165, 0x5b, v212
	v_cmp_lt_i32_e32 vcc, -1, v165
	s_nop 4
	v_cndmask_b32_e32 v114, v185, v114, vcc
	v_cmp_lt_i32_e32 vcc, 31, v165
	v_add_u32_e32 v165, 0x5a, v212
	s_nop 0
	v_cndmask_b32_e32 v98, v185, v98, vcc
	v_cmp_lt_i32_e32 vcc, -1, v165
	s_nop 1
	v_cndmask_b32_e32 v115, v185, v115, vcc
	v_cmp_lt_i32_e32 vcc, 31, v165
	v_add_u32_e32 v165, 0x59, v212
	s_nop 0
	v_cndmask_b32_e32 v99, v185, v99, vcc
	v_cmp_lt_i32_e32 vcc, -1, v165
	s_nop 1
	v_cndmask_b32_e32 v116, v185, v116, vcc
	v_cmp_lt_i32_e32 vcc, 31, v165
	v_add_u32_e32 v165, 0x58, v212
	s_nop 0
	v_cndmask_b32_e32 v100, v185, v100, vcc
	v_cmp_lt_i32_e32 vcc, -1, v165
	s_nop 1
	v_cndmask_b32_e32 v117, v185, v117, vcc
	v_cmp_lt_i32_e32 vcc, 31, v165
	v_add_u32_e32 v165, 0x53, v212
	s_nop 0
	v_cndmask_b32_e32 v101, v185, v101, vcc
	v_cmp_lt_i32_e32 vcc, -1, v165
	s_nop 1
	v_cndmask_b32_e32 v118, v185, v118, vcc
	v_cmp_lt_i32_e32 vcc, 31, v165
	v_add_u32_e32 v165, 0x52, v212
	s_nop 0
	v_cndmask_b32_e32 v102, v185, v102, vcc
	v_cmp_lt_i32_e32 vcc, -1, v165
	s_nop 1
	v_cndmask_b32_e32 v119, v185, v119, vcc
	v_cmp_lt_i32_e32 vcc, 31, v165
	v_add_u32_e32 v165, 0x51, v212
	s_nop 0
	v_cndmask_b32_e32 v103, v185, v103, vcc
	v_cmp_lt_i32_e32 vcc, -1, v165
	s_nop 1
	v_cndmask_b32_e32 v120, v185, v120, vcc
	v_cmp_lt_i32_e32 vcc, 31, v165
	v_add_u32_e32 v165, 0x50, v212
	s_nop 0
	v_cndmask_b32_e32 v104, v185, v104, vcc
	v_cmp_lt_i32_e32 vcc, -1, v165
	s_nop 1
	v_cndmask_b32_e32 v121, v185, v121, vcc
	v_cmp_lt_i32_e32 vcc, 31, v165
	v_add_u32_e32 v165, 0x4b, v212
	s_nop 0
	v_cndmask_b32_e32 v105, v185, v105, vcc
	v_cmp_lt_i32_e32 vcc, -1, v165
	s_nop 1
	v_cndmask_b32_e32 v122, v185, v122, vcc
	v_cmp_lt_i32_e32 vcc, 31, v165
	v_add_u32_e32 v165, 0x4a, v212
	s_nop 0
	v_cndmask_b32_e32 v106, v185, v106, vcc
	v_cmp_lt_i32_e32 vcc, -1, v165
	s_nop 1
	v_cndmask_b32_e32 v123, v185, v123, vcc
	v_cmp_lt_i32_e32 vcc, 31, v165
	v_add_u32_e32 v165, 0x49, v212
	s_nop 0
	v_cndmask_b32_e32 v107, v185, v107, vcc
	v_cmp_lt_i32_e32 vcc, -1, v165
	s_nop 1
	v_cndmask_b32_e32 v124, v185, v124, vcc
	v_cmp_lt_i32_e32 vcc, 31, v165
	v_add_u32_e32 v165, 0x48, v212
	s_nop 0
	v_cndmask_b32_e32 v108, v185, v108, vcc
	v_cmp_lt_i32_e32 vcc, -1, v165
	s_nop 1
	v_cndmask_b32_e32 v125, v185, v125, vcc
	v_cmp_lt_i32_e32 vcc, 31, v165
	v_add_u32_e32 v165, 0x43, v212
	s_nop 0
	v_cndmask_b32_e32 v109, v185, v109, vcc
	v_cmp_lt_i32_e32 vcc, -1, v165
	s_nop 1
	v_cndmask_b32_e32 v126, v185, v126, vcc
	v_cmp_lt_i32_e32 vcc, 31, v165
	v_add_u32_e32 v165, 0x42, v212
	s_nop 0
	v_cndmask_b32_e32 v110, v185, v110, vcc
	v_cmp_lt_i32_e32 vcc, -1, v165
	s_nop 1
	v_cndmask_b32_e32 v127, v185, v127, vcc
	v_cmp_lt_i32_e32 vcc, 31, v165
	v_add_u32_e32 v165, 0x41, v212
	s_nop 0
	v_cndmask_b32_e32 v111, v185, v111, vcc
	v_cmp_lt_i32_e32 vcc, -1, v165
	s_nop 1
	v_cndmask_b32_e32 v128, v185, v128, vcc
	v_cmp_lt_i32_e32 vcc, 31, v165
	v_add_u32_e32 v165, 64, v212
	s_nop 0
	v_cndmask_b32_e32 v112, v185, v112, vcc
	v_cmp_lt_i32_e32 vcc, -1, v165
	s_nop 1
	v_cndmask_b32_e32 v129, v185, v129, vcc
	v_cmp_lt_i32_e32 vcc, 31, v165
	s_nop 1
	v_cndmask_b32_e32 v113, v185, v113, vcc

.LBB0_1431:
	v_exp_f32_e32 v114, v114
	v_exp_f32_e32 v215, v98
	v_exp_f32_e32 v98, v115
	v_exp_f32_e32 v115, v99
	v_exp_f32_e32 v99, v116
	v_exp_f32_e32 v116, v100
	v_exp_f32_e32 v100, v117
	v_exp_f32_e32 v117, v101
	v_exp_f32_e32 v101, v118
	v_exp_f32_e32 v118, v102
	v_exp_f32_e32 v102, v119
	v_exp_f32_e32 v119, v103
	v_exp_f32_e32 v103, v120
	v_exp_f32_e32 v120, v104
	v_exp_f32_e32 v104, v121
	v_exp_f32_e32 v121, v105
	v_exp_f32_e32 v105, v122
	v_exp_f32_e32 v122, v106
	v_exp_f32_e32 v106, v123
	v_exp_f32_e32 v123, v107
	v_exp_f32_e32 v107, v124
	v_exp_f32_e32 v124, v108
	v_exp_f32_e32 v108, v125
	v_exp_f32_e32 v125, v109
	v_exp_f32_e32 v109, v126
	v_exp_f32_e32 v126, v110
	v_exp_f32_e32 v110, v127
	v_exp_f32_e32 v127, v111
	v_exp_f32_e32 v111, v128
	v_exp_f32_e32 v128, v112
	v_exp_f32_e32 v112, v129
	v_add_f32_e32 v129, v114, v215
	v_add_f32_e32 v213, v98, v115
	v_add_f32_e32 v214, v99, v116
	v_add_f32_e32 v216, v100, v117
	v_exp_f32_e32 v113, v113
	v_add_f32_e32 v129, v129, v101
	v_add_f32_e32 v213, v213, v102
	v_add_f32_e32 v214, v214, v103
	v_add_f32_e32 v216, v216, v104
	v_mov_b32_e32 v165, v163
	v_add_f32_e32 v129, v129, v118
	v_add_f32_e32 v213, v213, v119
	v_add_f32_e32 v214, v214, v120
	v_add_f32_e32 v216, v216, v121
	v_mov_b32_e32 v167, v163
	v_add_f32_e32 v129, v129, v105
	v_add_f32_e32 v213, v213, v106
	v_add_f32_e32 v214, v214, v107
	v_add_f32_e32 v216, v216, v108
	v_lshl_add_u64 v[168:169], v[168:169], 0, v[162:163]
	v_add_f32_e32 v129, v129, v122
	v_add_f32_e32 v213, v213, v123
	v_add_f32_e32 v214, v214, v124
	v_add_f32_e32 v216, v216, v125
	v_lshl_add_u64 v[170:171], v[170:171], 0, v[164:165]
	v_add_f32_e32 v129, v129, v109
	v_add_f32_e32 v213, v213, v110
	v_add_f32_e32 v214, v214, v111
	v_add_f32_e32 v216, v216, v112
	v_lshl_add_u64 v[172:173], v[172:173], 0, v[166:167]
	v_add_f32_e32 v129, v129, v126
	v_add_f32_e32 v213, v213, v127
	v_add_f32_e32 v214, v214, v128
	v_add_f32_e32 v216, v216, v113
	v_lshl_add_u64 v[180:181], v[174:175], 0, s[76:77]
	v_add_f32_e32 v129, v129, v213
	v_add_f32_e32 v213, v214, v216
	v_lshl_add_u64 v[178:179], v[176:177], 0, s[76:77]
	v_add_f32_e32 v213, v129, v213
	v_cvt_pk_bf16_f32 v98, v114, v98
	v_cvt_pk_bf16_f32 v99, v99, v100
	v_cvt_pk_bf16_f32 v100, v101, v102
	v_cvt_pk_bf16_f32 v101, v103, v104
	v_cvt_pk_bf16_f32 v102, v105, v106
	s_nop 0
	v_mov_b32_e32 v214, v213
	s_nop 1
	v_permlane32_swap_b32_e32 v213, v214
	v_cvt_pk_bf16_f32 v103, v107, v108
	v_cvt_pk_bf16_f32 v104, v109, v110
	v_cvt_pk_bf16_f32 v105, v111, v112
	v_cvt_pk_bf16_f32 v106, v215, v115
	v_cvt_pk_bf16_f32 v107, v116, v117
	v_cvt_pk_bf16_f32 v108, v118, v119
	v_cvt_pk_bf16_f32 v109, v120, v121
	v_cvt_pk_bf16_f32 v110, v122, v123
	v_cvt_pk_bf16_f32 v111, v124, v125
	v_cvt_pk_bf16_f32 v112, v126, v127
	v_cvt_pk_bf16_f32 v113, v128, v113
	v_permlane32_swap_b32_e32 v98, v100
	v_permlane32_swap_b32_e32 v99, v101
	v_permlane32_swap_b32_e32 v102, v104
	v_permlane32_swap_b32_e32 v103, v105
	v_permlane32_swap_b32_e32 v106, v108
	v_permlane32_swap_b32_e32 v107, v109
	v_permlane32_swap_b32_e32 v110, v112
	v_permlane32_swap_b32_e32 v111, v113
	s_add_i32 s13, s86, 0x0
	s_mov_b32 s14, m0
	s_mov_b32 m0, s13
	s_nop 0
	global_load_lds_dwordx4 v[174:175], off
	s_mov_b32 m0, s14
	ds_read_b64_tr_b16 v[114:115], v190 offset:0x4000
	ds_read_b64_tr_b16 v[116:117], v190 offset:0x4800
	ds_read_b64_tr_b16 v[118:119], v190 offset:0x5000
	ds_read_b64_tr_b16 v[120:121], v190 offset:0x5800
	ds_read_b64_tr_b16 v[122:123], v190 offset:0x6000
	ds_read_b64_tr_b16 v[124:125], v190 offset:0x6800
	ds_read_b64_tr_b16 v[126:127], v190 offset:0x7000
	ds_read_b64_tr_b16 v[128:129], v190 offset:0x7800
	ds_read_b64_tr_b16 v[216:217], v190 offset:0x4200
	ds_read_b64_tr_b16 v[218:219], v190 offset:0x4a00
	ds_read_b64_tr_b16 v[220:221], v190 offset:0x5200
	ds_read_b64_tr_b16 v[222:223], v190 offset:0x5a00
	ds_read_b64_tr_b16 v[224:225], v190 offset:0x6200
	ds_read_b64_tr_b16 v[226:227], v190 offset:0x6a00
	ds_read_b64_tr_b16 v[228:229], v190 offset:0x7200
	ds_read_b64_tr_b16 v[230:231], v190 offset:0x7a00
	s_waitcnt lgkmcnt(8)
	s_nop 0
	v_mfma_f32_32x32x16_bf16 v[18:33], v[98:101], v[114:117], v[18:33]
	v_mfma_f32_32x32x16_bf16 v[18:33], v[102:105], v[118:121], v[18:33]
	v_mfma_f32_32x32x16_bf16 v[18:33], v[106:109], v[122:125], v[18:33]
	v_mfma_f32_32x32x16_bf16 v[18:33], v[110:113], v[126:129], v[18:33]
	s_add_i32 s13, s3, 0x0
	s_mov_b32 s14, m0
	s_mov_b32 m0, s13
	s_nop 0
	global_load_lds_dwordx4 v[176:177], off
	s_mov_b32 m0, s14
	ds_read_b64_tr_b16 v[114:115], v190 offset:0x4400
	ds_read_b64_tr_b16 v[116:117], v190 offset:0x4c00
	ds_read_b64_tr_b16 v[118:119], v190 offset:0x5400
	ds_read_b64_tr_b16 v[120:121], v190 offset:0x5c00
	ds_read_b64_tr_b16 v[122:123], v190 offset:0x6400
	ds_read_b64_tr_b16 v[124:125], v190 offset:0x6c00
	ds_read_b64_tr_b16 v[126:127], v190 offset:0x7400
	ds_read_b64_tr_b16 v[128:129], v190 offset:0x7c00
	s_waitcnt lgkmcnt(8)
	v_mfma_f32_32x32x16_bf16 v[34:49], v[98:101], v[216:219], v[34:49]
	v_mfma_f32_32x32x16_bf16 v[34:49], v[102:105], v[220:223], v[34:49]
	v_mfma_f32_32x32x16_bf16 v[34:49], v[106:109], v[224:227], v[34:49]
	v_mfma_f32_32x32x16_bf16 v[34:49], v[110:113], v[228:231], v[34:49]
	ds_read_b64_tr_b16 v[216:217], v190 offset:0x4600
	ds_read_b64_tr_b16 v[218:219], v190 offset:0x4e00
	ds_read_b64_tr_b16 v[220:221], v190 offset:0x5600
	ds_read_b64_tr_b16 v[222:223], v190 offset:0x5e00
	ds_read_b64_tr_b16 v[224:225], v190 offset:0x6600
	ds_read_b64_tr_b16 v[226:227], v190 offset:0x6e00
	ds_read_b64_tr_b16 v[228:229], v190 offset:0x7600
	ds_read_b64_tr_b16 v[230:231], v190 offset:0x7e00
	s_waitcnt lgkmcnt(8)
	v_mfma_f32_32x32x16_bf16 v[50:65], v[98:101], v[114:117], v[50:65]
	v_mfma_f32_32x32x16_bf16 v[50:65], v[102:105], v[118:121], v[50:65]
	v_mfma_f32_32x32x16_bf16 v[50:65], v[106:109], v[122:125], v[50:65]
	v_mfma_f32_32x32x16_bf16 v[50:65], v[110:113], v[126:129], v[50:65]
	s_waitcnt lgkmcnt(0)
	v_mfma_f32_32x32x16_bf16 v[66:81], v[98:101], v[216:219], v[66:81]
	s_waitcnt vmcnt(0)
	s_cmp_lt_u32 s11, s10
	s_cselect_b64 s[0:1], -1, 0
	s_cmp_ge_u32 s11, s10
	s_barrier
	ds_read_b128 v[232:235], v194 offset:32768
	ds_read_b128 v[216:219], v194 offset:45056
	ds_read_b128 v[238:241], v195 offset:32768
	ds_read_b128 v[242:245], v195 offset:45056
	ds_read_b128 v[246:249], v196 offset:32768
	ds_read_b128 v[250:253], v196 offset:45056
	v_mfma_f32_32x32x16_bf16 v[66:81], v[102:105], v[220:223], v[66:81]
	v_mfma_f32_32x32x16_bf16 v[66:81], v[106:109], v[224:227], v[66:81]
	v_mfma_f32_32x32x16_bf16 v[66:81], v[110:113], v[228:231], v[66:81]
	s_cbranch_scc1 .LBB0_1433
	s_add_i32 s13, s86, 0x4000
	s_mov_b32 s14, m0
	s_mov_b32 m0, s13
	s_nop 0
	global_load_lds_dwordx4 v[180:181], off
	s_mov_b32 m0, s14
	s_add_i32 s13, s3, 0x4000
	s_mov_b32 s14, m0
	s_mov_b32 m0, s13
	s_nop 0
	global_load_lds_dwordx4 v[178:179], off
	s_mov_b32 m0, s14
	v_lshl_add_u64 v[174:175], v[174:175], 0, s[30:31]
	v_lshl_add_u64 v[176:177], v[176:177], 0, s[30:31]
	s_branch .LBB0_1434

.LBB0_1434:
	ds_read_b128 v[220:223], v193
	ds_read_b128 v[224:227], v193 offset:1024
	ds_read_b128 v[228:231], v193 offset:2048
	ds_read_b128 v[178:181], v193 offset:3072
	s_waitcnt lgkmcnt(9)
	v_mfma_f32_32x32x16_bf16 v[114:129], v[232:235], v[158:161], v[82:97]
	s_waitcnt lgkmcnt(8)
	v_mfma_f32_32x32x16_bf16 v[98:113], v[216:219], v[158:161], v[82:97]
	ds_read_b128 v[232:235], v197 offset:32768
	ds_read_b128 v[216:219], v197 offset:45056
	s_waitcnt lgkmcnt(9)
	v_mfma_f32_32x32x16_bf16 v[114:129], v[238:241], v[154:157], v[114:129]
	s_waitcnt lgkmcnt(8)
	v_mfma_f32_32x32x16_bf16 v[98:113], v[242:245], v[154:157], v[98:113]
	ds_read_b128 v[238:241], v194 offset:32896
	ds_read_b128 v[242:245], v194 offset:45184
	s_waitcnt lgkmcnt(9)
	v_mfma_f32_32x32x16_bf16 v[114:129], v[246:249], v[150:153], v[114:129]
	s_waitcnt lgkmcnt(8)
	v_mfma_f32_32x32x16_bf16 v[98:113], v[250:253], v[150:153], v[98:113]
	ds_read_b128 v[246:249], v195 offset:32896
	ds_read_b128 v[250:253], v195 offset:45184
	s_waitcnt lgkmcnt(5)
	v_mfma_f32_32x32x16_bf16 v[114:129], v[232:235], v[146:149], v[114:129]
	s_waitcnt lgkmcnt(4)
	v_mfma_f32_32x32x16_bf16 v[98:113], v[216:219], v[146:149], v[98:113]
	ds_read_b128 v[232:235], v196 offset:32896
	ds_read_b128 v[216:219], v196 offset:45184
	s_waitcnt lgkmcnt(5)
	v_mfma_f32_32x32x16_bf16 v[114:129], v[238:241], v[142:145], v[114:129]
	s_waitcnt lgkmcnt(4)
	v_mfma_f32_32x32x16_bf16 v[98:113], v[242:245], v[142:145], v[98:113]
	ds_read_b128 v[238:241], v197 offset:32896
	ds_read_b128 v[242:245], v197 offset:45184
	s_waitcnt lgkmcnt(5)
	v_mfma_f32_32x32x16_bf16 v[114:129], v[246:249], v[138:141], v[114:129]
	s_waitcnt lgkmcnt(4)
	v_mfma_f32_32x32x16_bf16 v[98:113], v[250:253], v[138:141], v[98:113]
	ds_read_b128 v[246:249], v194 offset:33024
	ds_read_b128 v[250:253], v194 offset:45312
	s_cmp_ge_u32 s11, s10
	s_cbranch_scc1 .Lspr_k1
	s_add_i32 s13, s74, 0xe000
	s_mov_b32 s14, m0
	s_mov_b32 m0, s13
	s_nop 0
	global_load_lds_dwordx4 v[168:169], off
	s_mov_b32 m0, s14
.Lspr_k1:
	s_waitcnt lgkmcnt(5)
	v_mfma_f32_32x32x16_bf16 v[114:129], v[232:235], v[134:137], v[114:129]
	s_waitcnt lgkmcnt(4)
	v_mfma_f32_32x32x16_bf16 v[98:113], v[216:219], v[134:137], v[98:113]
	ds_read_b128 v[232:235], v195 offset:33024
	ds_read_b128 v[216:219], v195 offset:45312
	s_waitcnt lgkmcnt(5)
	v_mfma_f32_32x32x16_bf16 v[114:129], v[238:241], v[130:133], v[114:129]
	s_waitcnt lgkmcnt(4)
	v_mfma_f32_32x32x16_bf16 v[98:113], v[242:245], v[130:133], v[98:113]
	ds_read_b128 v[238:241], v196 offset:33024
	ds_read_b128 v[242:245], v196 offset:45312
	s_waitcnt lgkmcnt(5)
	v_mfma_f32_32x32x16_bf16 v[114:129], v[246:249], v[220:223], v[114:129]
	s_waitcnt lgkmcnt(4)
	v_mfma_f32_32x32x16_bf16 v[98:113], v[250:253], v[220:223], v[98:113]
	ds_read_b128 v[246:249], v197 offset:33024
	ds_read_b128 v[250:253], v197 offset:45312
	s_waitcnt lgkmcnt(5)
	v_mfma_f32_32x32x16_bf16 v[114:129], v[232:235], v[224:227], v[114:129]
	s_waitcnt lgkmcnt(4)
	v_mfma_f32_32x32x16_bf16 v[98:113], v[216:219], v[224:227], v[98:113]
	s_waitcnt lgkmcnt(3)
	v_mfma_f32_32x32x16_bf16 v[114:129], v[238:241], v[228:231], v[114:129]
	s_waitcnt lgkmcnt(2)
	v_mfma_f32_32x32x16_bf16 v[98:113], v[242:245], v[228:231], v[98:113]
	s_waitcnt lgkmcnt(1)
	v_mfma_f32_32x32x16_bf16 v[114:129], v[246:249], v[178:181], v[114:129]
	s_waitcnt lgkmcnt(0)
	v_mfma_f32_32x32x16_bf16 v[98:113], v[250:253], v[178:181], v[98:113]
	s_cmp_ge_u32 s11, s10
	s_cbranch_scc1 .Lspr_k2
	s_add_i32 s13, s75, 0xe000
	s_mov_b32 s14, m0
	s_mov_b32 m0, s13
	s_nop 0
	global_load_lds_dwordx4 v[170:171], off
	s_mov_b32 m0, s14

.Lspr_k3:
	ds_read_b64_tr_b16 v[114:115], v190 offset:0
	ds_read_b64_tr_b16 v[116:117], v190 offset:0x800
	ds_read_b64_tr_b16 v[118:119], v190 offset:0x1000
	ds_read_b64_tr_b16 v[120:121], v190 offset:0x1800
	ds_read_b64_tr_b16 v[122:123], v190 offset:0x2000
	ds_read_b64_tr_b16 v[124:125], v190 offset:0x2800
	ds_read_b64_tr_b16 v[126:127], v190 offset:0x3000
	ds_read_b64_tr_b16 v[128:129], v190 offset:0x3800
	ds_read_b64_tr_b16 v[178:179], v190 offset:0x200
	ds_read_b64_tr_b16 v[180:181], v190 offset:0xa00
	ds_read_b64_tr_b16 v[214:215], v190 offset:0x1200
	ds_read_b64_tr_b16 v[216:217], v190 offset:0x1a00
	ds_read_b64_tr_b16 v[218:219], v190 offset:0x2200
	ds_read_b64_tr_b16 v[220:221], v190 offset:0x2a00
	ds_read_b64_tr_b16 v[222:223], v190 offset:0x3200
	ds_read_b64_tr_b16 v[224:225], v190 offset:0x3a00
	s_waitcnt lgkmcnt(8)
	s_nop 0
	v_mfma_f32_32x32x16_bf16 v[18:33], v[98:101], v[114:117], v[18:33]
	v_mfma_f32_32x32x16_bf16 v[18:33], v[102:105], v[118:121], v[18:33]
	v_mfma_f32_32x32x16_bf16 v[18:33], v[106:109], v[122:125], v[18:33]
	v_mfma_f32_32x32x16_bf16 v[18:33], v[110:113], v[126:129], v[18:33]
	ds_read_b64_tr_b16 v[114:115], v190 offset:0x400
	ds_read_b64_tr_b16 v[116:117], v190 offset:0xc00
	ds_read_b64_tr_b16 v[118:119], v190 offset:0x1400
	ds_read_b64_tr_b16 v[120:121], v190 offset:0x1c00
	ds_read_b64_tr_b16 v[122:123], v190 offset:0x2400
	ds_read_b64_tr_b16 v[124:125], v190 offset:0x2c00
	ds_read_b64_tr_b16 v[126:127], v190 offset:0x3400
	ds_read_b64_tr_b16 v[128:129], v190 offset:0x3c00
	s_waitcnt lgkmcnt(8)
	v_mfma_f32_32x32x16_bf16 v[34:49], v[98:101], v[178:181], v[34:49]
	v_mfma_f32_32x32x16_bf16 v[34:49], v[102:105], v[214:217], v[34:49]
	v_mfma_f32_32x32x16_bf16 v[34:49], v[106:109], v[218:221], v[34:49]
	v_mfma_f32_32x32x16_bf16 v[34:49], v[110:113], v[222:225], v[34:49]
	ds_read_b64_tr_b16 v[178:179], v190 offset:0x600
	ds_read_b64_tr_b16 v[180:181], v190 offset:0xe00
	ds_read_b64_tr_b16 v[214:215], v190 offset:0x1600
	ds_read_b64_tr_b16 v[216:217], v190 offset:0x1e00
	ds_read_b64_tr_b16 v[218:219], v190 offset:0x2600
	ds_read_b64_tr_b16 v[220:221], v190 offset:0x2e00
	ds_read_b64_tr_b16 v[222:223], v190 offset:0x3600
	ds_read_b64_tr_b16 v[224:225], v190 offset:0x3e00
	s_waitcnt lgkmcnt(8)
	v_mfma_f32_32x32x16_bf16 v[50:65], v[98:101], v[114:117], v[50:65]
	v_mfma_f32_32x32x16_bf16 v[50:65], v[102:105], v[118:121], v[50:65]
	v_mfma_f32_32x32x16_bf16 v[50:65], v[106:109], v[122:125], v[50:65]
	v_mfma_f32_32x32x16_bf16 v[50:65], v[110:113], v[126:129], v[50:65]
	s_waitcnt lgkmcnt(0)
	v_mfma_f32_32x32x16_bf16 v[66:81], v[98:101], v[178:181], v[66:81]
	s_waitcnt vmcnt(0)
	s_addk_i32 s12, 0x80
	s_add_i32 s8, s11, 2
	s_add_i32 s9, s11, 1
	v_add_u32_e32 v212, 0xffffff80, v212
	s_cmp_lt_u32 s9, s10
	v_mfma_f32_32x32x16_bf16 v[66:81], v[102:105], v[214:217], v[66:81]
	s_barrier
	ds_read_b128 v[178:181], v211
	ds_read_b128 v[214:217], v211 offset:12288
	ds_read_b128 v[238:241], v210
	ds_read_b128 v[242:245], v210 offset:12288
	ds_read_b128 v[246:249], v209
	ds_read_b128 v[250:253], v209 offset:12288
	v_mfma_f32_32x32x16_bf16 v[66:81], v[106:109], v[218:221], v[66:81]
	v_mfma_f32_32x32x16_bf16 v[66:81], v[110:113], v[222:225], v[66:81]
	s_cbranch_scc0 .LBB0_1442
	s_mov_b32 s11, s8
	s_branch .LBB0_1425
